# stick-breaking tile loop: 41 register copies forwarded to their readers and removed (after the packed-op split)
# speedup vs baseline: 1.0091x; 1.0091x over previous
.LBB0_465:
	s_cmp_ge_i32 s23, s4
	s_cselect_b64 s[16:17], -1, 0
	s_or_b64 s[16:17], s[16:17], s[14:15]
	s_and_b64 vcc, exec, s[16:17]
	s_cbranch_vccnz .LBB0_467
	v_add3_u32 v130, s18, v192, v205
	ds_read_b128 v[64:67], v130 offset:8704
	ds_read_b128 v[132:135], v130 offset:8736
	v_or_b32_e32 v163, s23, v200
	v_add3_u32 v207, s22, v204, v206
	s_waitcnt lgkmcnt(1)
	v_mfma_f32_32x32x16_bf16 v[66:81], v[64:67], v[82:85], 0
	s_waitcnt lgkmcnt(0)
	v_mfma_f32_32x32x16_bf16 v[66:81], v[132:135], v[86:89], v[66:81]
	ds_read_b128 v[132:135], v130 offset:8768
	ds_read_b128 v[136:139], v130 offset:8800
	s_waitcnt lgkmcnt(1)
	v_mfma_f32_32x32x16_bf16 v[66:81], v[132:135], v[90:93], v[66:81]
	s_waitcnt lgkmcnt(0)
	v_mfma_f32_32x32x16_bf16 v[66:81], v[136:139], v[94:97], v[66:81]
	ds_read_b128 v[132:135], v130 offset:8832
	ds_read_b128 v[136:139], v130 offset:8864
	s_waitcnt lgkmcnt(1)
	v_mfma_f32_32x32x16_bf16 v[66:81], v[132:135], v[98:101], v[66:81]
	s_waitcnt lgkmcnt(0)
	v_mfma_f32_32x32x16_bf16 v[66:81], v[136:139], v[102:105], v[66:81]
	ds_read_b128 v[132:135], v130 offset:8896
	ds_read_b128 v[136:139], v130 offset:8928
	ds_read_b128 v[208:211], v130 offset:224
	s_waitcnt lgkmcnt(2)
	v_mfma_f32_32x32x16_bf16 v[66:81], v[132:135], v[106:109], v[66:81]
	s_waitcnt lgkmcnt(1)
	v_mfma_f32_32x32x16_bf16 v[66:81], v[136:139], v[110:113], v[66:81]
	s_nop 11
	v_mov_b32_e32 v64, v66
	v_mov_b32_e32 v65, v68
	v_mov_b32_e32 v68, v67
	v_mul_f32_e32 v132, s68, v64
	v_mul_f32_e32 v133, s68, v65
	v_mov_b32_e32 v66, v70
	v_mul_f32_e32 v134, s68, v68
	v_mul_f32_e32 v135, s68, v69
	v_mul_f32_e64 v70, |v132|, s54
	v_mov_b32_e32 v67, v72
	v_mul_f32_e64 v72, |v134|, s54
	v_exp_f32_e32 v70, v70
	v_mul_f32_e64 v131, |v133|, s54
	v_exp_f32_e32 v72, v72
	v_mul_f32_e64 v138, |v135|, s54
	v_exp_f32_e32 v131, v131
	v_mul_f32_e32 v136, s68, v66
	v_mul_f32_e32 v137, s68, v67
	v_exp_f32_e32 v138, v138
	v_mul_f32_e64 v139, |v136|, s54
	v_add_f32_e32 v70, 1.0, v70
	v_exp_f32_e32 v139, v139
	v_add_f32_e32 v72, 1.0, v72
	v_add_f32_e32 v131, 1.0, v131
	v_add_f32_e32 v138, 1.0, v138
	v_log_f32_e32 v70, v70
	v_add_f32_e32 v139, 1.0, v139
	v_log_f32_e32 v72, v72
	v_log_f32_e32 v131, v131
	v_log_f32_e32 v138, v138
	v_mov_b32_e32 v142, v139
	v_mul_f32_e32 v139, 0x3f317217, v70
	v_mul_f32_e32 v140, 0x3f317217, v72
	v_fma_f32 v139, v70, s86, -v139
	v_mul_f32_e32 v141, 0x3f317217, v131
	v_fma_f32 v140, v72, s86, -v140
	v_fmac_f32_e32 v139, 0x3377d1cf, v70
	v_mul_f32_e32 v143, 0x3f317217, v138
	v_fma_f32 v141, v131, s86, -v141
	v_fmac_f32_e32 v140, 0x3377d1cf, v72
	v_fmac_f32_e32 v139, 0x3f317217, v70
	v_fma_f32 v143, v138, s86, -v143
	v_fmac_f32_e32 v141, 0x3377d1cf, v131
	v_fmac_f32_e32 v140, 0x3f317217, v72
	v_fmac_f32_e32 v143, 0x3377d1cf, v138
	v_fmac_f32_e32 v141, 0x3f317217, v131
	v_fmac_f32_e32 v143, 0x3f317217, v138
	v_min_f32_e32 v132, 0, v132
	v_min_f32_e32 v133, 0, v133
	v_sub_f32_e32 v166, v132, v139
	v_sub_f32_e32 v167, v133, v141
	v_fma_f32 v174, -v64, s68, v166
	v_fma_f32 v175, -v65, s68, v167
	v_log_f32_e32 v65, v142
	v_min_f32_e32 v134, 0, v134
	v_min_f32_e32 v135, 0, v135
	v_sub_f32_e32 v164, v134, v140
	v_sub_f32_e32 v165, v135, v143
	v_mov_b32_e32 v72, v71
	v_fma_f32 v172, -v68, s68, v164
	v_fma_f32 v173, -v69, s68, v165
	v_mul_f32_e32 v68, 0x3f317217, v65
	v_fma_f32 v70, v65, s86, -v68
	v_mul_f32_e32 v68, s68, v72
	v_mul_f32_e32 v69, s68, v73
	v_fmac_f32_e32 v70, 0x3377d1cf, v65
	v_mul_f32_e64 v71, |v68|, s54
	v_exp_f32_e32 v71, v71
	v_fmac_f32_e32 v70, 0x3f317217, v65
	v_mul_f32_e64 v131, |v137|, s54
	v_exp_f32_e32 v131, v131
	v_mov_b32_e32 v65, v70
	v_add_f32_e32 v70, 1.0, v71
	v_mul_f32_e64 v133, |v69|, s54
	v_exp_f32_e32 v133, v133
	v_log_f32_e32 v71, v70
	v_mov_b32_e32 v70, v65
	v_min_f32_e32 v64, 0, v136
	v_mul_f32_e32 v65, 0x3f317217, v71
	v_fma_f32 v65, v71, s86, -v65
	v_fmac_f32_e32 v65, 0x3377d1cf, v71
	v_fmac_f32_e32 v65, 0x3f317217, v71
	v_min_f32_e32 v68, 0, v68
	v_min_f32_e32 v69, 0, v69
	v_add_f32_e32 v71, 1.0, v131
	v_mov_b32_e32 v140, v78
	v_mov_b32_e32 v141, v80
	v_log_f32_e32 v71, v71
	v_mov_b32_e32 v132, v65
	v_min_f32_e32 v65, 0, v137
	v_mul_f32_e32 v131, 0x3f317217, v71
	v_fma_f32 v131, v71, s86, -v131
	v_fmac_f32_e32 v131, 0x3377d1cf, v71
	v_fmac_f32_e32 v131, 0x3f317217, v71
	v_mul_f32_e32 v142, s68, v140
	v_mul_f32_e32 v143, s68, v141
	v_mov_b32_e32 v80, v79
	v_mov_b32_e32 v71, v131
	v_add_f32_e32 v131, 1.0, v133
	v_sub_f32_e32 v168, v64, v70
	v_sub_f32_e32 v169, v65, v71
	v_log_f32_e32 v131, v131
	v_fma_f32 v176, -v66, s68, v168
	v_fma_f32 v177, -v67, s68, v169
	v_mul_f32_e32 v144, s68, v80
	v_mul_f32_e32 v145, s68, v81
	v_mul_f32_e32 v64, 0x3f317217, v131
	v_fma_f32 v70, v131, s86, -v64
	v_mov_b32_e32 v64, v74
	v_mul_f32_e32 v66, s68, v64
	v_mul_f32_e32 v67, s68, v76
	v_fmac_f32_e32 v70, 0x3377d1cf, v131
	v_mul_f32_e64 v71, |v66|, s54
	v_exp_f32_e32 v71, v71
	v_fmac_f32_e32 v70, 0x3f317217, v131
	v_min_f32_e32 v66, 0, v66
	v_mov_b32_e32 v133, v70
	v_add_f32_e32 v70, 1.0, v71
	v_sub_f32_e32 v170, v68, v132
	v_sub_f32_e32 v171, v69, v133
	ds_read_b128 v[132:135], v130 offset:32
	v_log_f32_e32 v70, v70
	v_fma_f32 v178, -v72, s68, v170
	v_fma_f32 v179, -v73, s68, v171
	v_mul_f32_e64 v73, |v67|, s54
	v_exp_f32_e32 v73, v73
	v_mul_f32_e32 v68, 0x3f317217, v70
	v_fma_f32 v71, v70, s86, -v68
	v_mul_f32_e32 v68, s68, v75
	v_mul_f32_e32 v69, s68, v77
	v_fmac_f32_e32 v71, 0x3377d1cf, v70
	v_mul_f32_e64 v72, |v68|, s54
	v_exp_f32_e32 v72, v72
	v_fmac_f32_e32 v71, 0x3f317217, v70
	v_mul_f32_e64 v74, |v69|, s54
	v_exp_f32_e32 v74, v74
	v_mov_b32_e32 v70, v71
	v_add_f32_e32 v71, 1.0, v72
	v_min_f32_e32 v67, 0, v67
	v_min_f32_e32 v68, 0, v68
	v_log_f32_e32 v71, v71
	v_mov_b32_e32 v70, v70
	v_min_f32_e32 v69, 0, v69
	v_mul_f32_e32 v72, 0x3f317217, v71
	v_fma_f32 v72, v71, s86, -v72
	v_fmac_f32_e32 v72, 0x3377d1cf, v71
	v_fmac_f32_e32 v72, 0x3f317217, v71
	s_nop 1
	v_mov_b32_e32 v71, v72
	v_add_f32_e32 v72, 1.0, v73
	s_nop 1
	v_log_f32_e32 v73, v72
	v_mov_b32_e32 v72, v71
	v_mul_f32_e32 v71, 0x3f317217, v73
	v_fma_f32 v71, v73, s86, -v71
	v_fmac_f32_e32 v71, 0x3377d1cf, v73
	v_fmac_f32_e32 v71, 0x3f317217, v73
	s_nop 1
	v_add_f32_e32 v73, 1.0, v74
	v_sub_f32_e32 v180, v66, v70
	v_sub_f32_e32 v181, v67, v71
	v_mul_f32_e64 v70, |v143|, s54
	v_log_f32_e32 v73, v73
	v_fma_f32 v184, -v64, s68, v180
	v_fma_f32 v185, -v76, s68, v181
	v_mul_f32_e64 v65, |v142|, s54
	v_exp_f32_e32 v65, v65
	v_mul_f32_e32 v64, 0x3f317217, v73
	v_fma_f32 v64, v73, s86, -v64
	v_fmac_f32_e32 v64, 0x3377d1cf, v73
	v_fmac_f32_e32 v64, 0x3f317217, v73
	v_exp_f32_e32 v131, v70
	v_mov_b32_e32 v73, v64
	v_add_f32_e32 v64, 1.0, v65
	v_mul_f32_e64 v66, |v144|, s54
	v_exp_f32_e32 v66, v66
	v_log_f32_e32 v64, v64
	v_sub_f32_e32 v182, v68, v72
	v_sub_f32_e32 v183, v69, v73
	v_add_f32_e32 v131, 1.0, v131
	v_fma_f32 v186, -v75, s68, v182
	v_fma_f32 v187, -v77, s68, v183
	v_mul_f32_e32 v65, 0x3f317217, v64
	v_fma_f32 v65, v64, s86, -v65
	v_fmac_f32_e32 v65, 0x3377d1cf, v64
	v_fmac_f32_e32 v65, 0x3f317217, v64
	v_min_f32_e32 v142, 0, v142
	v_min_f32_e32 v143, 0, v143
	v_mov_b32_e32 v64, v65
	v_add_f32_e32 v65, 1.0, v66
	v_min_f32_e32 v144, 0, v144
	v_log_f32_e32 v68, v65
	v_mov_b32_e32 v146, v64
	ds_read_b128 v[64:67], v130
	v_mul_f32_e32 v69, 0x3f317217, v68
	v_fma_f32 v69, v68, s86, -v69
	v_fmac_f32_e32 v69, 0x3377d1cf, v68
	v_fmac_f32_e32 v69, 0x3f317217, v68
	s_nop 0
	v_mov_b32_e32 v147, v69
	s_waitcnt lgkmcnt(0)
	v_mfma_f32_32x32x16_bf16 v[64:79], v[64:67], v[82:85], 0
	v_mov_b32_e32 v148, v147
	s_nop 0
	ds_read_b128 v[136:139], v130 offset:64
	v_log_f32_e32 v131, v131
	v_mfma_f32_32x32x16_bf16 v[64:79], v[132:135], v[86:89], v[64:79]
	v_mul_f32_e32 v132, 0x3f317217, v131
	v_fma_f32 v147, v131, s86, -v132
	ds_read_b128 v[132:135], v130 offset:96
	v_fmac_f32_e32 v147, 0x3377d1cf, v131
	v_fmac_f32_e32 v147, 0x3f317217, v131
	s_waitcnt lgkmcnt(1)
	v_mfma_f32_32x32x16_bf16 v[64:79], v[136:139], v[90:93], v[64:79]
	v_mul_f32_e64 v137, |v145|, s54
	v_exp_f32_e32 v149, v137
	ds_read_b128 v[136:139], v130 offset:128
	s_waitcnt lgkmcnt(1)
	v_mfma_f32_32x32x16_bf16 v[64:79], v[132:135], v[94:97], v[64:79]
	v_add_f32_e32 v131, 1.0, v149
	v_add_f32_e64 v188, v142, -v146
	v_add_f32_e64 v189, v143, -v147
	v_min_f32_e32 v145, 0, v145
	ds_read_b128 v[132:135], v130 offset:160
	s_waitcnt lgkmcnt(1)
	v_mfma_f32_32x32x16_bf16 v[64:79], v[136:139], v[98:101], v[64:79]
	v_log_f32_e32 v131, v131
	v_fma_f32 v212, -v140, s68, v188
	v_fma_f32 v213, -v141, s68, v189
	v_mul_f32_e32 v136, 0x3f317217, v131
	v_fma_f32 v140, v131, s86, -v136
	ds_read_b128 v[136:139], v130 offset:192
	s_waitcnt lgkmcnt(1)
	v_mfma_f32_32x32x16_bf16 v[64:79], v[132:135], v[102:105], v[64:79]
	v_fmac_f32_e32 v140, 0x3377d1cf, v131
	v_fmac_f32_e32 v140, 0x3f317217, v131
	s_nop 0
	s_waitcnt lgkmcnt(0)
	v_mfma_f32_32x32x16_bf16 v[64:79], v[136:139], v[106:109], v[64:79]
	v_add_f32_e64 v190, v144, -v148
	v_add_f32_e64 v191, v145, -v140
	ds_read_b64_tr_b16 v[146:147], v207 offset:45056
	ds_read_b64_tr_b16 v[142:143], v207 offset:45120
	ds_read_b64_tr_b16 v[138:139], v207 offset:45184
	ds_read_b64_tr_b16 v[134:135], v207 offset:45248
	ds_read_b64_tr_b16 v[148:149], v207 offset:47616
	ds_read_b64_tr_b16 v[144:145], v207 offset:47680
	ds_read_b64_tr_b16 v[140:141], v207 offset:47744
	ds_read_b64_tr_b16 v[136:137], v207 offset:47808
	ds_read_b64_tr_b16 v[130:131], v207 offset:50176
	ds_read_b64_tr_b16 v[132:133], v207 offset:52736
	v_fma_f32 v216, -v80, s68, v190
	v_fma_f32 v217, -v81, s68, v191
	v_or_b32_e32 v80, 34, v163
	v_cmp_lt_i32_e64 s[26:27], v80, v153
	v_mfma_f32_32x32x16_bf16 v[64:79], v[208:211], v[110:113], v[64:79]
	v_or_b32_e32 v208, 32, v163
	v_cmp_lt_i32_e64 s[30:31], v208, v152
	v_or_b32_e32 v208, 33, v163
	v_cmp_lt_i32_e64 s[40:41], v208, v152
	v_cndmask_b32_e64 v80, 0, v174, s[30:31]
	v_or_b32_e32 v174, 35, v163
	v_cmp_lt_i32_e64 s[38:39], v174, v153
	v_cndmask_b32_e64 v81, 0, v175, s[26:27]
	v_cndmask_b32_e64 v174, 0, v172, s[40:41]
	v_cndmask_b32_e64 v175, 0, v173, s[38:39]
	v_add_f32_e32 v80, v80, v174
	v_add_f32_e32 v81, v81, v175
	v_or_b32_e32 v208, 40, v163
	v_add_f32_e32 v172, v80, v81
	v_add_f32_e32 v173, v81, v80
	v_cmp_lt_i32_e64 s[22:23], v208, v152
	v_or_b32_e32 v173, 42, v163
	v_cmp_lt_i32_e64 s[18:19], v173, v153
	v_or_b32_e32 v173, 43, v163
	v_or_b32_e32 v208, 41, v163
	v_cmp_lt_i32_e64 s[28:29], v173, v153
	v_or_b32_e32 v173, 50, v163
	v_cmp_lt_i32_e64 s[34:35], v208, v152
	v_or_b32_e32 v208, 48, v163
	v_cmp_lt_i32_e32 vcc, v173, v153
	v_or_b32_e32 v173, 51, v163
	v_cmp_lt_i32_e64 s[42:43], v208, v152
	v_or_b32_e32 v208, 49, v163
	v_cmp_lt_i32_e64 s[16:17], v173, v153
	v_or_b32_e32 v173, 58, v163
	v_cmp_lt_i32_e64 s[44:45], v208, v152
	v_or_b32_e32 v208, 56, v163
	v_cmp_lt_i32_e64 s[14:15], v173, v153
	v_or_b32_e32 v173, 59, v163
	v_or_b32_e32 v210, 57, v163
	v_cmp_lt_i32_e64 s[36:37], v208, v152
	v_cmp_lt_i32_e64 s[20:21], v173, v153
	v_cmp_lt_i32_e64 s[24:25], v210, v152
	v_cndmask_b32_e32 v185, 0, v185, vcc
	v_cndmask_b32_e64 v184, 0, v184, s[42:43]
	v_cndmask_b32_e64 v187, 0, v187, s[16:17]
	v_cndmask_b32_e64 v186, 0, v186, s[44:45]
	v_cndmask_b32_e64 v209, 0, v213, s[14:15]
	v_cndmask_b32_e64 v208, 0, v212, s[36:37]
	v_cndmask_b32_e64 v211, 0, v217, s[20:21]
	v_cndmask_b32_e64 v210, 0, v216, s[24:25]
	v_add_f32_e32 v184, v184, v186
	v_add_f32_e32 v185, v185, v187
	v_add_f32_e32 v208, v208, v210
	v_add_f32_e32 v209, v209, v211
	v_add_f32_e32 v240, v184, v185
	v_add_f32_e32 v241, v185, v184
	v_add_f32_e32 v212, v208, v209
	v_add_f32_e32 v213, v209, v208
	ds_bpermute_b32 v216, v235, v212
	ds_bpermute_b32 v184, v235, v240
	v_cndmask_b32_e64 v177, 0, v177, s[18:19]
	s_waitcnt lgkmcnt(1)
	v_add_f32_e32 v208, v212, v216
	s_waitcnt lgkmcnt(0)
	v_cndmask_b32_e64 v213, 0, v184, s[10:11]
	v_add_f32_e32 v208, v213, v208
	v_add_f32_e32 v245, v162, v208
	v_add_f32_e32 v246, v186, v185
	v_add_f32_e32 v247, v180, v245
	v_add_f32_e32 v182, v182, v245
	v_add_f32_e32 v180, v246, v247
	v_mul_f32_e32 v180, 0x3fb8aa3b, v180
	v_exp_f32_e32 v180, v180
	v_add_f32_e32 v182, v185, v182
	v_mul_f32_e32 v182, 0x3fb8aa3b, v182
	v_cndmask_b32_e64 v176, 0, v176, s[22:23]
	v_cndmask_b32_e64 v179, 0, v179, s[28:29]
	v_cndmask_b32_e64 v178, 0, v178, s[34:35]
	v_exp_f32_e32 v182, v182
	v_add_f32_e32 v176, v176, v178
	v_add_f32_e32 v177, v177, v179
	v_cndmask_b32_e64 v213, 0, v180, s[42:43]
	v_add_f32_e32 v180, v181, v245
	v_add_f32_e32 v242, v176, v177
	v_add_f32_e32 v243, v177, v176
	v_add_f32_e32 v180, v187, v180
	ds_bpermute_b32 v80, v235, v172
	ds_bpermute_b32 v176, v235, v242
	v_mul_f32_e32 v180, 0x3fb8aa3b, v180
	v_cndmask_b32_e64 v215, 0, v182, s[44:45]
	v_exp_f32_e32 v239, v180
	v_add_f32_e32 v180, v183, v245
	v_add_f32_e32 v182, v184, v216
	v_add_f32_e32 v183, v240, v212
	v_add_f32_e32 v180, 0, v180
	v_add_f32_e32 v181, v242, v183
	v_add_f32_e32 v181, v181, v216
	v_add_f32_e32 v181, v181, v184
	v_cndmask_b32_e64 v173, 0, v216, s[10:11]
	s_waitcnt lgkmcnt(1)
	v_cndmask_b32_e64 v208, 0, v80, s[10:11]
	v_mul_f32_e32 v180, 0x3fb8aa3b, v180
	s_waitcnt lgkmcnt(0)
	v_add_f32_e32 v181, v181, v176
	v_exp_f32_e32 v241, v180
	v_add_f32_e32 v180, v162, v173
	v_add_f32_e32 v173, v183, v216
	v_add_f32_e32 v181, v208, v181
	v_cndmask_b32_e64 v186, 0, v176, s[10:11]
	v_add_f32_e32 v173, v173, v184
	v_add_f32_e32 v185, v162, v181
	v_add_f32_e32 v173, v186, v173
	v_add_f32_e32 v164, v164, v185
	v_add_f32_e32 v186, v174, v81
	v_add_f32_e32 v187, v166, v185
	v_add_f32_e32 v81, v81, v164
	v_add_f32_e32 v164, v167, v185
	v_add_f32_e32 v165, v165, v185
	v_add_f32_e32 v166, v186, v187
	v_add_f32_e32 v164, v175, v164
	v_add_f32_e32 v165, 0, v165
	v_mul_f32_e32 v166, 0x3fb8aa3b, v166
	v_mul_f32_e32 v164, 0x3fb8aa3b, v164
	v_mul_f32_e32 v165, 0x3fb8aa3b, v165
	v_exp_f32_e32 v166, v166
	v_exp_f32_e32 v164, v164
	v_exp_f32_e32 v165, v165
	v_cndmask_b32_e64 v174, 0, v166, s[30:31]
	v_cndmask_b32_e64 v175, 0, v164, s[26:27]
	v_cndmask_b32_e64 v181, 0, v165, s[38:39]
	v_add_f32_e32 v165, v162, v173
	v_add_f32_e32 v166, v178, v177
	v_add_f32_e32 v167, v168, v165
	v_mul_f32_e32 v81, 0x3fb8aa3b, v81
	v_add_f32_e32 v164, v166, v167
	v_add_f32_e32 v166, v170, v165
	v_add_f32_e32 v167, v169, v165
	v_add_f32_e32 v165, v171, v165
	v_add_f32_e32 v166, v177, v166
	v_add_f32_e32 v167, v179, v167
	v_add_f32_e32 v165, 0, v165
	v_mul_f32_e32 v164, 0x3fb8aa3b, v164
	v_mul_f32_e32 v166, 0x3fb8aa3b, v166
	v_mul_f32_e32 v167, 0x3fb8aa3b, v167
	v_mul_f32_e32 v165, 0x3fb8aa3b, v165
	v_exp_f32_e32 v81, v81
	v_exp_f32_e32 v164, v164
	v_exp_f32_e32 v166, v166
	v_exp_f32_e32 v167, v167
	v_exp_f32_e32 v165, v165
	v_cndmask_b32_e64 v81, 0, v81, s[40:41]
	v_cndmask_b32_e64 v168, 0, v164, s[22:23]
	v_cndmask_b32_e64 v166, 0, v166, s[34:35]
	v_cndmask_b32_e64 v167, 0, v167, s[18:19]
	v_cndmask_b32_e64 v169, 0, v165, s[28:29]
	v_cvt_pk_bf16_f32 v164, v174, v81
	v_cvt_pk_bf16_f32 v165, v175, v181
	v_cvt_pk_bf16_f32 v166, v168, v166
	v_cvt_pk_bf16_f32 v167, v167, v169
	s_nop 0
	s_nop 0
	v_mfma_f32_32x32x16_bf16 v[48:63], v[146:149], v[164:167], v[48:63]
	v_add_f32_e64 v146, v180, v188
	v_add_f32_e64 v147, v210, v209
	v_add_f32_e32 v81, v146, v147
	v_mul_f32_e32 v81, 0x3fb8aa3b, v81
	v_exp_f32_e32 v81, v81
	v_cndmask_b32_e32 v146, 0, v239, vcc
	v_cndmask_b32_e64 v81, 0, v81, s[36:37]
	v_mfma_f32_32x32x16_bf16 v[32:47], v[142:145], v[164:167], v[32:47]
	v_add_f32_e32 v143, v180, v190
	v_add_f32_e32 v144, v180, v189
	v_add_f32_e32 v143, v143, v209
	v_mul_f32_e32 v143, 0x3fb8aa3b, v143
	v_exp_f32_e32 v143, v143
	v_cndmask_b32_e64 v142, 0, v241, s[16:17]
	v_mfma_f32_32x32x16_bf16 v[16:31], v[138:141], v[164:167], v[16:31]
	v_add_f32_e32 v139, v180, v191
	v_add_f32_e32 v138, v144, v211
	v_add_f32_e32 v139, 0, v139
	v_mul_f32_e32 v138, 0x3fb8aa3b, v138
	v_mul_f32_e32 v139, 0x3fb8aa3b, v139
	v_exp_f32_e32 v138, v138
	v_exp_f32_e32 v139, v139
	v_mfma_f32_32x32x16_bf16 v[0:15], v[134:137], v[164:167], v[0:15]
	v_cndmask_b32_e64 v136, 0, v143, s[24:25]
	v_cndmask_b32_e64 v137, 0, v138, s[14:15]
	v_cndmask_b32_e64 v138, 0, v139, s[20:21]
	v_cvt_pk_bf16_f32 v134, v213, v215
	v_cvt_pk_bf16_f32 v135, v146, v142
	v_cvt_pk_bf16_f32 v136, v81, v136
	v_cvt_pk_bf16_f32 v137, v137, v138
	ds_read_b64_tr_b16 v[138:139], v207 offset:50240
	ds_read_b64_tr_b16 v[142:143], v207 offset:50304
	ds_read_b64_tr_b16 v[146:147], v207 offset:50368
	ds_read_b64_tr_b16 v[140:141], v207 offset:52800
	ds_read_b64_tr_b16 v[144:145], v207 offset:52864
	ds_read_b64_tr_b16 v[148:149], v207 offset:52928
	v_mfma_f32_32x32x16_bf16 v[48:63], v[130:133], v[134:137], v[48:63]
	v_mov_b32_e32 v130, v64
	v_mov_b32_e32 v131, v68
	v_mul_f32_e64 v132, v130, s68
	v_mul_f32_e64 v133, v131, s68
	v_mul_f32_e64 v64, |v132|, s54
	v_exp_f32_e32 v64, v64
	v_add_f32_e32 v80, v80, v176
	v_add_f32_e32 v81, v172, v242
	s_waitcnt lgkmcnt(2)
	v_mfma_f32_32x32x16_bf16 v[32:47], v[138:141], v[134:137], v[32:47]
	v_add_f32_e64 v80, v80, v182
	v_add_f32_e64 v81, v81, v183
	v_add_f32_e32 v64, 1.0, v64
	s_nop 1
	v_log_f32_e32 v138, v64
	v_min_f32_e32 v64, 0, v132
	s_waitcnt lgkmcnt(1)
	v_mfma_f32_32x32x16_bf16 v[16:31], v[142:145], v[134:137], v[16:31]
	v_mul_f32_e64 v143, |v133|, s54
	v_mul_f32_e32 v68, 0x3f317217, v138
	v_fma_f32 v132, v138, s86, -v68
	v_mov_b32_e32 v68, v65
	v_fmac_f32_e32 v132, 0x3377d1cf, v138
	v_fmac_f32_e32 v132, 0x3f317217, v138
	s_waitcnt lgkmcnt(0)
	v_mfma_f32_32x32x16_bf16 v[0:15], v[146:149], v[134:137], v[0:15]
	v_mul_f32_e64 v134, v68, s68
	v_mul_f32_e64 v135, v69, s68
	v_mul_f32_e64 v65, |v134|, s54
	v_exp_f32_e32 v65, v65
	v_mov_b32_e32 v137, v70
	v_exp_f32_e32 v143, v143
	v_min_f32_e32 v134, 0, v134
	v_add_f32_e32 v65, 1.0, v65
	v_add_f32_e32 v143, 1.0, v143
	s_nop 0
	v_log_f32_e32 v65, v65
	s_nop 0
	v_mul_f32_e32 v136, 0x3f317217, v65
	v_fma_f32 v140, v65, s86, -v136
	v_mov_b32_e32 v136, v66
	v_mul_f32_e32 v138, s68, v136
	v_mul_f32_e32 v139, s68, v137
	v_fmac_f32_e32 v140, 0x3377d1cf, v65
	v_mul_f32_e64 v66, |v138|, s54
	v_exp_f32_e32 v66, v66
	v_fmac_f32_e32 v140, 0x3f317217, v65
	v_min_f32_e32 v138, 0, v138
	v_add_f32_e32 v66, 1.0, v66
	v_mov_b32_e32 v65, v140
	s_nop 1
	v_log_f32_e32 v142, v66
	v_mov_b32_e32 v70, v67
	v_mul_f32_e32 v140, s68, v70
	v_mul_f32_e32 v141, s68, v71
	v_mul_f32_e64 v67, |v140|, s54
	v_exp_f32_e32 v67, v67
	v_mov_b32_e32 v66, v65
	v_mul_f32_e32 v65, 0x3f317217, v142
	v_fma_f32 v65, v142, s86, -v65
	v_fmac_f32_e32 v65, 0x3377d1cf, v142
	v_fmac_f32_e32 v65, 0x3f317217, v142
	v_add_f32_e32 v67, 1.0, v67
	v_min_f32_e32 v140, 0, v140
	s_nop 1
	v_log_f32_e32 v67, v67
	v_mov_b32_e32 v142, v65
	v_mul_f32_e32 v65, 0x3f317217, v67
	v_fma_f32 v65, v67, s86, -v65
	v_fmac_f32_e32 v65, 0x3377d1cf, v67
	v_fmac_f32_e32 v65, 0x3f317217, v67
	s_nop 1
	s_nop 0
	v_log_f32_e32 v143, v143
	v_mov_b32_e32 v144, v65
	v_min_f32_e32 v65, 0, v133
	v_or_b32_e32 v67, 8, v163
	v_mul_f32_e32 v133, 0x3f317217, v143
	v_fma_f32 v133, v143, s86, -v133
	v_fmac_f32_e32 v133, 0x3377d1cf, v143
	v_fmac_f32_e32 v133, 0x3f317217, v143
	s_nop 1
	v_sub_f32_e32 v64, v64, v132
	v_sub_f32_e32 v65, v65, v133
	v_mul_f32_e64 v132, |v135|, s54
	v_exp_f32_e32 v132, v132
	v_cmp_lt_i32_e32 vcc, v67, v153
	v_fma_f32 v130, -v130, s68, v64
	v_fma_f32 v131, -v131, s68, v65
	v_cmp_lt_i32_e64 s[14:15], v163, v152
	v_add_f32_e32 v67, 1.0, v132
	s_nop 0
	v_cndmask_b32_e64 v146, 0, v130, s[14:15]
	v_min_f32_e32 v135, 0, v135
	v_log_f32_e32 v67, v67
	v_cndmask_b32_e32 v147, 0, v131, vcc
	v_or_b32_e32 v131, 1, v163
	v_or_b32_e32 v130, 9, v163
	v_mul_f32_e32 v132, 0x3f317217, v67
	v_fma_f32 v132, v67, s86, -v132
	v_fmac_f32_e32 v132, 0x3377d1cf, v67
	v_fmac_f32_e32 v132, 0x3f317217, v67
	s_nop 1
	v_mov_b32_e32 v67, v132
	v_mul_f32_e64 v132, |v139|, s54
	v_sub_f32_e32 v66, v134, v66
	v_sub_f32_e32 v67, v135, v67
	v_exp_f32_e32 v134, v132
	v_fma_f32 v68, -v68, s68, v66
	v_fma_f32 v69, -v69, s68, v67
	v_cmp_lt_i32_e64 s[18:19], v131, v152
	v_cmp_lt_i32_e64 s[16:17], v130, v153
	v_min_f32_e32 v139, 0, v139
	v_cndmask_b32_e64 v132, 0, v68, s[18:19]
	v_add_f32_e32 v68, 1.0, v134
	v_cndmask_b32_e64 v133, 0, v69, s[16:17]
	v_or_b32_e32 v135, 2, v163
	v_log_f32_e32 v68, v68
	v_cmp_lt_i32_e64 s[24:25], v135, v152
	v_or_b32_e32 v134, 10, v163
	v_mul_f32_e32 v69, 0x3f317217, v68
	v_fma_f32 v69, v68, s86, -v69
	v_fmac_f32_e32 v69, 0x3377d1cf, v68
	v_fmac_f32_e32 v69, 0x3f317217, v68
	s_nop 1
	v_sub_f32_e32 v68, v138, v142
	v_sub_f32_e32 v69, v139, v69
	v_cmp_lt_i32_e64 s[22:23], v134, v153
	v_fma_f32 v130, -v136, s68, v68
	v_fma_f32 v131, -v137, s68, v69
	v_mul_f32_e64 v136, |v141|, s54
	v_exp_f32_e32 v136, v136
	v_cndmask_b32_e64 v142, 0, v130, s[24:25]
	v_cndmask_b32_e64 v143, 0, v131, s[22:23]
	v_mul_f32_e32 v134, s68, v72
	v_mul_f32_e32 v135, s68, v73
	v_add_f32_e32 v130, 1.0, v136
	v_mul_f32_e64 v138, |v134|, s54
	v_exp_f32_e32 v138, v138
	v_log_f32_e32 v130, v130
	v_or_b32_e32 v136, 11, v163
	v_or_b32_e32 v137, 3, v163
	v_cmp_lt_i32_e64 s[34:35], v137, v152
	v_mul_f32_e32 v131, 0x3f317217, v130
	v_fma_f32 v131, v130, s86, -v131
	v_fmac_f32_e32 v131, 0x3377d1cf, v130
	v_fmac_f32_e32 v131, 0x3f317217, v130
	v_min_f32_e32 v134, 0, v134
	v_min_f32_e32 v141, 0, v141
	v_cmp_lt_i32_e64 s[26:27], v136, v153
	v_add_f32_e32 v136, 1.0, v138
	v_sub_f32_e32 v130, v140, v144
	v_sub_f32_e32 v131, v141, v131
	v_log_f32_e32 v136, v136
	v_mul_f32_e64 v138, |v135|, s54
	v_exp_f32_e32 v138, v138
	v_min_f32_e32 v135, 0, v135
	v_mul_f32_e32 v137, 0x3f317217, v136
	v_fma_f32 v137, v136, s86, -v137
	v_fmac_f32_e32 v137, 0x3377d1cf, v136
	v_fmac_f32_e32 v137, 0x3f317217, v136
	v_or_b32_e32 v140, 16, v163
	v_cmp_lt_i32_e64 s[36:37], v140, v152
	v_mov_b32_e32 v136, v137
	v_add_f32_e32 v137, 1.0, v138
	v_fma_f32 v70, -v70, s68, v130
	v_fma_f32 v71, -v71, s68, v131
	s_nop 0
	v_log_f32_e32 v137, v137
	v_mov_b32_e32 v136, v136
	v_cndmask_b32_e64 v71, 0, v71, s[26:27]
	v_mul_f32_e32 v138, 0x3f317217, v137
	v_fma_f32 v138, v137, s86, -v138
	v_fmac_f32_e32 v138, 0x3377d1cf, v137
	v_fmac_f32_e32 v138, 0x3f317217, v137
	v_cndmask_b32_e64 v70, 0, v70, s[34:35]
	s_nop 0
	v_sub_f32_e32 v134, v134, v136
	v_sub_f32_e32 v135, v135, v138
	v_mul_f32_e32 v136, s68, v74
	v_mul_f32_e32 v137, s68, v75
	v_or_b32_e32 v138, 17, v163
	v_mul_f32_e64 v139, |v136|, s54
	v_exp_f32_e32 v139, v139
	v_cmp_lt_i32_e64 s[20:21], v138, v153
	v_mul_f32_e64 v140, |v137|, s54
	v_exp_f32_e32 v140, v140
	v_add_f32_e32 v138, 1.0, v139
	v_min_f32_e32 v136, 0, v136
	v_min_f32_e32 v137, 0, v137
	v_log_f32_e32 v138, v138
	v_fma_f32 v72, -v72, s68, v134
	v_fma_f32 v73, -v73, s68, v135
	v_mul_f32_e32 v139, 0x3f317217, v138
	v_fma_f32 v139, v138, s86, -v139
	v_fmac_f32_e32 v139, 0x3377d1cf, v138
	v_fmac_f32_e32 v139, 0x3f317217, v138
	v_cndmask_b32_e64 v73, 0, v73, s[20:21]
	v_cndmask_b32_e64 v72, 0, v72, s[36:37]
	v_mov_b32_e32 v138, v139
	v_add_f32_e32 v139, 1.0, v140
	s_nop 1
	v_log_f32_e32 v139, v139
	v_mov_b32_e32 v138, v138
	v_mul_f32_e32 v140, 0x3f317217, v139
	v_fma_f32 v140, v139, s86, -v140
	v_fmac_f32_e32 v140, 0x3377d1cf, v139
	v_fmac_f32_e32 v140, 0x3f317217, v139
	s_nop 1
	v_mov_b32_e32 v139, v140
	v_or_b32_e32 v140, 18, v163
	v_cmp_lt_i32_e64 s[30:31], v140, v152
	v_add_f32_e32 v140, v142, v70
	v_add_f32_e32 v141, v143, v71
	v_mov_b32_e32 v142, v76
	v_mov_b32_e32 v143, v78
	v_mul_f32_e32 v144, s68, v142
	v_mul_f32_e32 v145, s68, v143
	v_sub_f32_e32 v136, v136, v138
	v_sub_f32_e32 v137, v137, v139
	v_mul_f32_e64 v76, |v144|, s54
	v_exp_f32_e32 v78, v76
	v_or_b32_e32 v138, 19, v163
	v_fma_f32 v74, -v74, s68, v136
	v_fma_f32 v75, -v75, s68, v137
	v_cmp_lt_i32_e64 s[28:29], v138, v153
	v_cndmask_b32_e64 v138, 0, v74, s[30:31]
	v_mul_f32_e64 v149, |v145|, s54
	v_cndmask_b32_e64 v139, 0, v75, s[28:29]
	v_add_f32_e32 v74, v146, v132
	v_add_f32_e32 v75, v147, v133
	v_exp_f32_e32 v149, v149
	v_add_f32_e32 v146, v74, v140
	v_add_f32_e32 v147, v75, v141
	v_add_f32_e32 v74, 1.0, v78
	ds_bpermute_b32 v148, v235, v147
	ds_bpermute_b32 v76, v235, v146
	v_log_f32_e32 v75, v74
	s_nop 0
	v_mul_f32_e32 v78, 0x3f317217, v75
	v_add_f32_e32 v164, v72, v73
	v_add_f32_e32 v165, v73, v75
	v_min_f32_e32 v74, 0, v144
	v_fma_f32 v144, v75, s86, -v78
	v_mov_b32_e32 v78, v77
	v_mul_f32_e32 v166, s68, v78
	v_mul_f32_e32 v167, s68, v79
	v_fmac_f32_e32 v144, 0x3377d1cf, v75
	v_mul_f32_e64 v77, |v166|, s54
	v_exp_f32_e32 v77, v77
	v_fmac_f32_e32 v144, 0x3f317217, v75
	v_min_f32_e32 v166, 0, v166
	v_add_f32_e32 v77, 1.0, v77
	v_or_b32_e32 v165, 24, v163
	v_cmp_lt_i32_e64 s[42:43], v165, v152
	v_log_f32_e32 v77, v77
	v_mov_b32_e32 v144, v144
	v_mul_f32_e32 v75, 0x3f317217, v77
	v_fma_f32 v75, v77, s86, -v75
	v_fmac_f32_e32 v75, 0x3377d1cf, v77
	v_fmac_f32_e32 v75, 0x3f317217, v77
	s_nop 1
	v_mov_b32_e32 v168, v75
	v_add_f32_e32 v75, 1.0, v149
	v_or_b32_e32 v149, 26, v163
	s_nop 0
	v_log_f32_e32 v77, v75
	v_min_f32_e32 v75, 0, v145
	v_mul_f32_e32 v145, 0x3f317217, v77
	v_fma_f32 v145, v77, s86, -v145
	v_fmac_f32_e32 v145, 0x3377d1cf, v77
	v_fmac_f32_e32 v145, 0x3f317217, v77
	s_nop 1
	v_mov_b32_e32 v145, v145
	v_mul_f32_e64 v77, |v167|, s54
	v_exp_f32_e32 v77, v77
	v_sub_f32_e32 v74, v74, v144
	v_sub_f32_e32 v75, v75, v145
	v_min_f32_e32 v167, 0, v167
	v_cmp_lt_i32_e64 s[38:39], v149, v153
	v_add_f32_e32 v77, 1.0, v77
	v_or_b32_e32 v149, 27, v163
	v_or_b32_e32 v163, 25, v163
	v_log_f32_e32 v77, v77
	v_fma_f32 v142, -v142, s68, v74
	v_fma_f32 v143, -v143, s68, v75
	v_mul_f32_e32 v144, 0x3f317217, v77
	v_fma_f32 v144, v77, s86, -v144
	v_fmac_f32_e32 v144, 0x3377d1cf, v77
	v_fmac_f32_e32 v144, 0x3f317217, v77
	v_cndmask_b32_e64 v143, 0, v143, s[38:39]
	v_cndmask_b32_e64 v142, 0, v142, s[42:43]
	v_mov_b32_e32 v169, v144
	v_sub_f32_e32 v144, v166, v168
	v_sub_f32_e32 v145, v167, v169
	v_cmp_lt_i32_e64 s[40:41], v149, v153
	v_fma_f32 v78, -v78, s68, v144
	v_fma_f32 v79, -v79, s68, v145
	v_cmp_lt_i32_e64 s[44:45], v163, v152
	v_cndmask_b32_e64 v167, 0, v79, s[40:41]
	v_mov_b32_e32 v168, v132
	v_cndmask_b32_e64 v166, 0, v78, s[44:45]
	v_add_f32_e32 v142, v142, v166
	v_add_f32_e32 v143, v143, v167
	v_add_f32_e32 v170, v138, v139
	v_add_f32_e32 v171, v139, v133
	v_add_f32_e32 v164, v164, v170
	v_add_f32_e32 v165, v142, v143
	ds_bpermute_b32 v149, v235, v165
	ds_bpermute_b32 v77, v235, v164
	v_add_f32_e32 v78, v146, v146
	v_add_f32_e32 v79, v146, v147
	v_mov_b32_e32 v169, v64
	v_mov_b32_e32 v64, v133
	v_add_f32_e32 v132, v164, v165
	v_add_f32_e32 v133, v165, v164
	s_waitcnt lgkmcnt(1)
	v_add_f32_e32 v142, v165, v149
	s_waitcnt lgkmcnt(0)
	v_cndmask_b32_e64 v146, 0, v77, s[10:11]
	v_add_f32_e32 v142, v146, v142
	v_add_f32_e32 v146, v132, v149
	v_add_f32_e32 v147, v147, v132
	v_add_f32_e32 v146, v146, v77
	v_cndmask_b32_e64 v163, 0, v148, s[10:11]
	v_add_f32_e32 v147, v147, v149
	v_add_f32_e32 v146, v163, v146
	v_add_f32_e32 v147, v147, v77
	v_cndmask_b32_e64 v163, 0, v76, s[10:11]
	v_add_f32_e32 v76, v76, v148
	v_add_f32_e32 v77, v77, v149
	v_mov_b32_e32 v78, v80
	v_add_f32_e32 v147, v147, v148
	v_add_f32_e32 v77, v76, v77
	v_add_f32_e32 v76, v76, v76
	v_pk_mov_b32 v[80:81], v[80:81], v[132:133] op_sel:[1,0]
	v_add_f32_e32 v147, v163, v147
	v_add_f32_e32 v78, v78, v80
	v_add_f32_e32 v79, v79, v81
	v_mov_b32_e32 v163, v77
	v_add_f32_e32 v80, v162, v78
	v_add_f32_e32 v81, v163, v79
	v_add_f32_e32 v77, v80, v147
	v_add_f32_e32 v78, v168, v140
	v_add_f32_e32 v79, v169, v77
	v_add_f32_e32 v68, v68, v77
	v_add_f32_e32 v76, v78, v79
	v_mul_f32_e32 v76, 0x3fb8aa3b, v76
	v_exp_f32_e32 v76, v76
	v_add_f32_e32 v66, v66, v77
	v_add_f32_e32 v68, v70, v68
	v_add_f32_e32 v70, v130, v77
	v_cndmask_b32_e64 v78, 0, v76, s[14:15]
	v_add_f32_e32 v77, v80, v146
	v_add_f32_e32 v66, v140, v66
	v_add_f32_e32 v64, v64, v141
	v_add_f32_e32 v65, v65, v77
	v_mul_f32_e32 v66, 0x3fb8aa3b, v66
	v_add_f32_e32 v64, v64, v65
	v_add_f32_e32 v65, v67, v77
	v_exp_f32_e32 v66, v66
	v_add_f32_e32 v65, v141, v65
	v_mul_f32_e32 v64, 0x3fb8aa3b, v64
	v_mul_f32_e32 v65, 0x3fb8aa3b, v65
	v_exp_f32_e32 v64, v64
	v_exp_f32_e32 v65, v65
	v_cndmask_b32_e64 v79, 0, v66, s[18:19]
	v_add_f32_e32 v66, v69, v77
	v_add_f32_e32 v66, v71, v66
	v_mul_f32_e32 v66, 0x3fb8aa3b, v66
	v_cndmask_b32_e32 v71, 0, v64, vcc
	v_cndmask_b32_e64 v76, 0, v65, s[16:17]
	v_add_f32_e32 v171, v80, v142
	v_pk_mov_b32 v[64:65], v[72:73], v[134:135] op_sel:[1,0]
	v_exp_f32_e32 v66, v66
	v_add_f32_e32 v67, v131, v77
	v_add_f32_e32 v64, v64, v170
	v_add_f32_e32 v65, v65, v171
	v_add_f32_e32 v67, 0, v67
	v_add_f32_e32 v64, v64, v65
	v_add_f32_e32 v65, v135, v171
	v_mul_f32_e32 v67, 0x3fb8aa3b, v67
	v_mul_f32_e32 v64, 0x3fb8aa3b, v64
	v_add_f32_e32 v65, v170, v65
	v_exp_f32_e32 v67, v67
	v_exp_f32_e32 v64, v64
	v_mul_f32_e32 v65, 0x3fb8aa3b, v65
	v_add_f32_e32 v70, 0, v70
	v_cndmask_b32_e64 v77, 0, v66, s[22:23]
	v_exp_f32_e32 v140, v65
	v_add_f32_e32 v65, v136, v171
	v_add_f32_e32 v66, v137, v171
	v_mul_f32_e32 v68, 0x3fb8aa3b, v68
	v_mul_f32_e32 v70, 0x3fb8aa3b, v70
	v_add_f32_e32 v65, v139, v65
	v_add_f32_e32 v66, 0, v66
	v_exp_f32_e32 v68, v68
	v_exp_f32_e32 v70, v70
	v_mul_f32_e32 v65, 0x3fb8aa3b, v65
	v_mul_f32_e32 v66, 0x3fb8aa3b, v66
	v_cndmask_b32_e64 v131, 0, v67, s[26:27]
	v_exp_f32_e32 v139, v66
	v_exp_f32_e32 v141, v65
	v_cndmask_b32_e64 v146, 0, v64, s[36:37]
	ds_read_b64_tr_b16 v[64:65], v207 offset:34816
	ds_read_b64_tr_b16 v[66:67], v207 offset:37376
	v_cndmask_b32_e64 v138, 0, v149, s[10:11]
	v_add_f32_e32 v72, v80, v138
	v_mov_b32_e32 v142, v74
	v_cndmask_b32_e64 v130, 0, v68, s[24:25]
	v_cndmask_b32_e64 v70, 0, v70, s[34:35]
	v_add_f32_e32 v68, v72, v142
	v_add_f32_e32 v69, v166, v143
	v_cndmask_b32_e64 v74, 0, v139, s[28:29]
	v_add_f32_e32 v73, v68, v69
	v_cvt_pk_bf16_f32 v68, v78, v79
	v_cvt_pk_bf16_f32 v69, v130, v70
	v_cvt_pk_bf16_f32 v70, v71, v76
	v_cvt_pk_bf16_f32 v71, v77, v131
	ds_read_b64_tr_b16 v[76:77], v207 offset:34880
	ds_read_b64_tr_b16 v[130:131], v207 offset:34944
	ds_read_b64_tr_b16 v[134:135], v207 offset:35008
	ds_read_b64_tr_b16 v[78:79], v207 offset:37440
	ds_read_b64_tr_b16 v[132:133], v207 offset:37504
	ds_read_b64_tr_b16 v[136:137], v207 offset:37568
	s_waitcnt lgkmcnt(6)
	v_mfma_f32_32x32x16_bf16 v[48:63], v[64:67], v[68:71], v[48:63]
	v_mul_f32_e32 v64, 0x3fb8aa3b, v73
	v_exp_f32_e32 v64, v64
	v_add_f32_e32 v65, v72, v75
	v_add_f32_e32 v65, v65, v167
	v_mul_f32_e32 v65, 0x3fb8aa3b, v65
	v_cndmask_b32_e64 v139, 0, v64, s[42:43]
	v_add_f32_e32 v64, v72, v144
	v_exp_f32_e32 v75, v65
	v_add_f32_e32 v65, v72, v145
	v_add_f32_e32 v64, v64, v143
	v_add_f32_e32 v65, 0, v65
	v_mul_f32_e32 v64, 0x3fb8aa3b, v64
	v_mul_f32_e32 v65, 0x3fb8aa3b, v65
	v_exp_f32_e32 v64, v64
	v_exp_f32_e32 v72, v65
	s_waitcnt lgkmcnt(2)
	v_mfma_f32_32x32x16_bf16 v[32:47], v[76:79], v[68:71], v[32:47]
	v_cndmask_b32_e64 v73, 0, v140, s[20:21]
	v_cndmask_b32_e64 v138, 0, v141, s[30:31]
	v_cndmask_b32_e64 v76, 0, v64, s[44:45]
	v_cndmask_b32_e64 v72, 0, v72, s[40:41]
	ds_read_b64_tr_b16 v[64:65], v207 offset:39936
	ds_read_b64_tr_b16 v[66:67], v207 offset:42496
	v_add_f32_e32 v162, v80, v81
	s_mov_b32 s14, 0xc2480000
	s_waitcnt lgkmcnt(3)
	v_mfma_f32_32x32x16_bf16 v[16:31], v[130:133], v[68:71], v[16:31]
	v_cmp_gt_f32_e32 vcc, s14, v162
	s_cmp_eq_u64 vcc, exec
	s_cselect_b64 s[14:15], -1, 0
	s_waitcnt lgkmcnt(2)
	v_mfma_f32_32x32x16_bf16 v[0:15], v[134:137], v[68:71], v[0:15]
	v_cndmask_b32_e64 v71, 0, v75, s[38:39]
	v_cvt_pk_bf16_f32 v68, v146, v73
	v_cvt_pk_bf16_f32 v69, v138, v74
	v_cvt_pk_bf16_f32 v70, v139, v76
	v_cvt_pk_bf16_f32 v71, v71, v72
	ds_read_b64_tr_b16 v[72:73], v207 offset:40000
	ds_read_b64_tr_b16 v[76:77], v207 offset:40064
	ds_read_b64_tr_b16 v[130:131], v207 offset:40128
	ds_read_b64_tr_b16 v[74:75], v207 offset:42560
	ds_read_b64_tr_b16 v[78:79], v207 offset:42624
	ds_read_b64_tr_b16 v[132:133], v207 offset:42688
	s_waitcnt lgkmcnt(6)
	v_mfma_f32_32x32x16_bf16 v[48:63], v[64:67], v[68:71], v[48:63]
	s_waitcnt lgkmcnt(2)
	v_mfma_f32_32x32x16_bf16 v[32:47], v[72:75], v[68:71], v[32:47]
	s_waitcnt lgkmcnt(1)
	v_mfma_f32_32x32x16_bf16 v[16:31], v[76:79], v[68:71], v[16:31]
	s_waitcnt lgkmcnt(0)
	v_mfma_f32_32x32x16_bf16 v[0:15], v[130:133], v[68:71], v[0:15]
